# P3 RWKV prep: token shift of r,k,v restructured from 24 serial iterations into 3 batches of 8 rows with all loads in flight, mu loaded once per batch
# baseline (speedup 1.0000x reference)
; __device__ __forceinline__ float bf_lo(unsigned u) { return __uint_as_float(u << 16); }
; __device__ __forceinline__ float bf_hi(unsigned u) { return __uint_as_float(u & 0xffff0000u); }
; __device__ __forceinline__ unsigned pk2(float lo, float hi) { return pg8::cvt_pk_bf16(lo, hi); }
; __global__ void __launch_bounds__(NT, 2) mk_fwd(Args args) {
;     ...
;                     for (int op = tid; op < 3 * 32 * 128; op += NT) {
;                         const int which = op >> 12, tl = (op >> 7) & 31, c8 = (op & 127) * 8; const int t = t0 + mt * 32 + tl; const bool first = (t & (SEQ - 1)) == 0;
;                         const bf16* cp = P + (size_t)t * NINP + 2048 + which * 1024 + c8;
;                         const u32x4 cu = *(const u32x4*)cp; u32x4 pr = (u32x4){0u, 0u, 0u, 0u}; if (!first) pr = *(const u32x4*)(cp - NINP);
;                         const f32x4 m0 = *(const f32x4*)(mu + which * 1024 + c8), m1 = *(const f32x4*)(mu + which * 1024 + c8 + 4);
;                         u32x4 o;
;                         { float a = bf_lo(cu.x), b = bf_hi(cu.x); a += (bf_lo(pr.x) - a) * m0.x; b += (bf_hi(pr.x) - b) * m0.y; o.x = pk2(a, b); }
;                         { float a = bf_lo(cu.y), b = bf_hi(cu.y); a += (bf_lo(pr.y) - a) * m0.z; b += (bf_hi(pr.y) - b) * m0.w; o.y = pk2(a, b); }
;                         { float a = bf_lo(cu.z), b = bf_hi(cu.z); a += (bf_lo(pr.z) - a) * m1.x; b += (bf_hi(pr.z) - b) * m1.y; o.z = pk2(a, b); }
;                         { float a = bf_lo(cu.w), b = bf_hi(cu.w); a += (bf_lo(pr.w) - a) * m1.z; b += (bf_hi(pr.w) - b) * m1.w; o.w = pk2(a, b); }
;                         if (which == 0) *(u32x4*)(RR + (size_t)t * 1024 + c8) = o;
.LBB0_353:
	s_xor_b64 s[0:1], s[8:9], -1
	s_or_b32 s33, s69, s68
	s_mov_b64 s[8:9], 0
	v_mov_b32_e32 v12, v205
	v_mov_b32_e32 v13, v204
	v_mov_b32_e32 v14, v168
	s_waitcnt lgkmcnt(0)
	s_barrier
	v_and_b32_e32 v227, 0x7f, v168
	v_lshlrev_b32_e32 v228, 5, v227
	v_lshlrev_b32_e32 v227, 4, v227
	v_mul_u32_u24_e32 v229, 0x810, v204
	v_add_u32_e32 v229, v229, v227
	v_add_u32_e32 v229, 0xa000, v229
	v_or_b32_e32 v230, s33, v204
	s_movk_i32 s10, 0x2c00
	v_mul_lo_u32 v211, v230, s10
	v_lshlrev_b32_e32 v219, 11, v230
	v_add_u32_e32 v211, v211, v227
	v_add_u32_e32 v219, v219, v227
	v_add_u32_e32 v230, 4, v230
	v_mul_lo_u32 v212, v230, s10
	v_lshlrev_b32_e32 v220, 11, v230
	v_add_u32_e32 v212, v212, v227
	v_add_u32_e32 v220, v220, v227
	v_add_u32_e32 v230, 4, v230
	v_mul_lo_u32 v213, v230, s10
	v_lshlrev_b32_e32 v221, 11, v230
	v_add_u32_e32 v213, v213, v227
	v_add_u32_e32 v221, v221, v227
	v_add_u32_e32 v230, 4, v230
	v_mul_lo_u32 v214, v230, s10
	v_lshlrev_b32_e32 v222, 11, v230
	v_add_u32_e32 v214, v214, v227
	v_add_u32_e32 v222, v222, v227
	v_add_u32_e32 v230, 4, v230
	v_mul_lo_u32 v215, v230, s10
	v_lshlrev_b32_e32 v223, 11, v230
	v_add_u32_e32 v215, v215, v227
	v_add_u32_e32 v223, v223, v227
	v_add_u32_e32 v230, 4, v230
	v_mul_lo_u32 v216, v230, s10
	v_lshlrev_b32_e32 v224, 11, v230
	v_add_u32_e32 v216, v216, v227
	v_add_u32_e32 v224, v224, v227
	v_add_u32_e32 v230, 4, v230
	v_mul_lo_u32 v217, v230, s10
	v_lshlrev_b32_e32 v225, 11, v230
	v_add_u32_e32 v217, v217, v227
	v_add_u32_e32 v225, v225, v227
	v_add_u32_e32 v230, 4, v230
	v_mul_lo_u32 v218, v230, s10
	v_lshlrev_b32_e32 v226, 11, v230
	v_add_u32_e32 v218, v218, v227
	v_add_u32_e32 v226, v226, v227
	v_cmp_ne_u32_e64 s[42:43], 0, v204
	s_and_b32 s11, s33, 0x7ff
	s_cmp_lg_u32 s11, 0
	s_cselect_b64 s[42:43], -1, s[42:43]
	s_add_u32 s44, s20, 0x1000
	s_addc_u32 s45, s21, 0
	s_sub_u32 s10, s44, 0x2c00
	s_subb_u32 s11, s45, 0
	global_load_dwordx4 v[136:139], v228, s[58:59]
	global_load_dwordx4 v[140:143], v228, s[58:59] offset:16
	v_mov_b32_e32 v32, 0
	v_mov_b32_e32 v33, 0
	v_mov_b32_e32 v34, 0
	v_mov_b32_e32 v35, 0
	global_load_dwordx4 v[0:3], v211, s[44:45]
	s_and_saveexec_b64 s[8:9], s[42:43]
	global_load_dwordx4 v[32:35], v211, s[10:11]
	s_or_b64 exec, exec, s[8:9]
	global_load_dwordx4 v[4:7], v212, s[44:45]
	global_load_dwordx4 v[36:39], v212, s[10:11]
	global_load_dwordx4 v[8:11], v213, s[44:45]
	global_load_dwordx4 v[40:43], v213, s[10:11]
	global_load_dwordx4 v[12:15], v214, s[44:45]
	global_load_dwordx4 v[44:47], v214, s[10:11]
	global_load_dwordx4 v[16:19], v215, s[44:45]
	global_load_dwordx4 v[48:51], v215, s[10:11]
	global_load_dwordx4 v[20:23], v216, s[44:45]
	global_load_dwordx4 v[52:55], v216, s[10:11]
	global_load_dwordx4 v[24:27], v217, s[44:45]
	global_load_dwordx4 v[56:59], v217, s[10:11]
	global_load_dwordx4 v[28:31], v218, s[44:45]
	global_load_dwordx4 v[60:63], v218, s[10:11]
	s_waitcnt vmcnt(14)
	v_lshlrev_b32_e32 v144, 16, v0
	v_and_b32_e32 v145, 0xffff0000, v0
	v_lshlrev_b32_e32 v152, 16, v32
	v_and_b32_e32 v153, 0xffff0000, v32
	v_lshlrev_b32_e32 v146, 16, v1
	v_and_b32_e32 v147, 0xffff0000, v1
	v_lshlrev_b32_e32 v154, 16, v33
	v_and_b32_e32 v155, 0xffff0000, v33
	v_lshlrev_b32_e32 v148, 16, v2
	v_and_b32_e32 v149, 0xffff0000, v2
	v_lshlrev_b32_e32 v156, 16, v34
	v_and_b32_e32 v157, 0xffff0000, v34
	v_lshlrev_b32_e32 v150, 16, v3
	v_and_b32_e32 v151, 0xffff0000, v3
	v_lshlrev_b32_e32 v158, 16, v35
	v_and_b32_e32 v159, 0xffff0000, v35
	v_sub_f32_e32 v152, v152, v144
	v_sub_f32_e32 v153, v153, v145
	v_sub_f32_e32 v154, v154, v146
	v_sub_f32_e32 v155, v155, v147
	v_sub_f32_e32 v156, v156, v148
	v_sub_f32_e32 v157, v157, v149
	v_sub_f32_e32 v158, v158, v150
	v_sub_f32_e32 v159, v159, v151
	v_fmac_f32_e32 v144, v136, v152
	v_fmac_f32_e32 v145, v137, v153
	v_fmac_f32_e32 v146, v138, v154
	v_fmac_f32_e32 v147, v139, v155
	v_fmac_f32_e32 v148, v140, v156
	v_fmac_f32_e32 v149, v141, v157
	v_fmac_f32_e32 v150, v142, v158
	v_fmac_f32_e32 v151, v143, v159
	v_cvt_pk_bf16_f32 v0, v144, v145
	v_cvt_pk_bf16_f32 v1, v146, v147
	v_cvt_pk_bf16_f32 v2, v148, v149
	v_cvt_pk_bf16_f32 v3, v150, v151
	s_nop 0
	global_store_dwordx4 v219, v[0:3], s[28:29]
	s_waitcnt vmcnt(13)
	v_lshlrev_b32_e32 v144, 16, v4
	v_and_b32_e32 v145, 0xffff0000, v4
	v_lshlrev_b32_e32 v152, 16, v36
	v_and_b32_e32 v153, 0xffff0000, v36
	v_lshlrev_b32_e32 v146, 16, v5
	v_and_b32_e32 v147, 0xffff0000, v5
	v_lshlrev_b32_e32 v154, 16, v37
	v_and_b32_e32 v155, 0xffff0000, v37
	v_lshlrev_b32_e32 v148, 16, v6
	v_and_b32_e32 v149, 0xffff0000, v6
	v_lshlrev_b32_e32 v156, 16, v38
	v_and_b32_e32 v157, 0xffff0000, v38
	v_lshlrev_b32_e32 v150, 16, v7
	v_and_b32_e32 v151, 0xffff0000, v7
	v_lshlrev_b32_e32 v158, 16, v39
	v_and_b32_e32 v159, 0xffff0000, v39
	v_sub_f32_e32 v152, v152, v144
	v_sub_f32_e32 v153, v153, v145
	v_sub_f32_e32 v154, v154, v146
	v_sub_f32_e32 v155, v155, v147
	v_sub_f32_e32 v156, v156, v148
	v_sub_f32_e32 v157, v157, v149
	v_sub_f32_e32 v158, v158, v150
	v_sub_f32_e32 v159, v159, v151
	v_fmac_f32_e32 v144, v136, v152
	v_fmac_f32_e32 v145, v137, v153
	v_fmac_f32_e32 v146, v138, v154
	v_fmac_f32_e32 v147, v139, v155
	v_fmac_f32_e32 v148, v140, v156
	v_fmac_f32_e32 v149, v141, v157
	v_fmac_f32_e32 v150, v142, v158
	v_fmac_f32_e32 v151, v143, v159
	v_cvt_pk_bf16_f32 v4, v144, v145
	v_cvt_pk_bf16_f32 v5, v146, v147
	v_cvt_pk_bf16_f32 v6, v148, v149
	v_cvt_pk_bf16_f32 v7, v150, v151
	s_nop 0
	global_store_dwordx4 v220, v[4:7], s[28:29]
	s_waitcnt vmcnt(12)
; __device__ __forceinline__ float bf_lo(unsigned u) { return __uint_as_float(u << 16); }
; __device__ __forceinline__ float bf_hi(unsigned u) { return __uint_as_float(u & 0xffff0000u); }
; __device__ __forceinline__ unsigned pk2(float lo, float hi) { return pg8::cvt_pk_bf16(lo, hi); }
; __global__ void __launch_bounds__(NT, 2) mk_fwd(Args args) {
;     ...
;                         const u32x4 cu = *(const u32x4*)cp; u32x4 pr = (u32x4){0u, 0u, 0u, 0u}; if (!first) pr = *(const u32x4*)(cp - NINP);
;                         const f32x4 m0 = *(const f32x4*)(mu + which * 1024 + c8), m1 = *(const f32x4*)(mu + which * 1024 + c8 + 4);
;                         u32x4 o;
;                         { float a = bf_lo(cu.x), b = bf_hi(cu.x); a += (bf_lo(pr.x) - a) * m0.x; b += (bf_hi(pr.x) - b) * m0.y; o.x = pk2(a, b); }
;                         { float a = bf_lo(cu.y), b = bf_hi(cu.y); a += (bf_lo(pr.y) - a) * m0.z; b += (bf_hi(pr.y) - b) * m0.w; o.y = pk2(a, b); }
;                         { float a = bf_lo(cu.z), b = bf_hi(cu.z); a += (bf_lo(pr.z) - a) * m1.x; b += (bf_hi(pr.z) - b) * m1.y; o.z = pk2(a, b); }
;                         { float a = bf_lo(cu.w), b = bf_hi(cu.w); a += (bf_lo(pr.w) - a) * m1.z; b += (bf_hi(pr.w) - b) * m1.w; o.w = pk2(a, b); }
;                         if (which == 0) *(u32x4*)(RR + (size_t)t * 1024 + c8) = o;
	v_lshlrev_b32_e32 v144, 16, v8
	v_and_b32_e32 v145, 0xffff0000, v8
	v_lshlrev_b32_e32 v152, 16, v40
	v_and_b32_e32 v153, 0xffff0000, v40
	v_lshlrev_b32_e32 v146, 16, v9
	v_and_b32_e32 v147, 0xffff0000, v9
	v_lshlrev_b32_e32 v154, 16, v41
	v_and_b32_e32 v155, 0xffff0000, v41
	v_lshlrev_b32_e32 v148, 16, v10
	v_and_b32_e32 v149, 0xffff0000, v10
	v_lshlrev_b32_e32 v156, 16, v42
	v_and_b32_e32 v157, 0xffff0000, v42
	v_lshlrev_b32_e32 v150, 16, v11
	v_and_b32_e32 v151, 0xffff0000, v11
	v_lshlrev_b32_e32 v158, 16, v43
	v_and_b32_e32 v159, 0xffff0000, v43
	v_sub_f32_e32 v152, v152, v144
	v_sub_f32_e32 v153, v153, v145
	v_sub_f32_e32 v154, v154, v146
	v_sub_f32_e32 v155, v155, v147
	v_sub_f32_e32 v156, v156, v148
	v_sub_f32_e32 v157, v157, v149
	v_sub_f32_e32 v158, v158, v150
	v_sub_f32_e32 v159, v159, v151
	v_fmac_f32_e32 v144, v136, v152
	v_fmac_f32_e32 v145, v137, v153
	v_fmac_f32_e32 v146, v138, v154
	v_fmac_f32_e32 v147, v139, v155
	v_fmac_f32_e32 v148, v140, v156
	v_fmac_f32_e32 v149, v141, v157
	v_fmac_f32_e32 v150, v142, v158
	v_fmac_f32_e32 v151, v143, v159
	v_cvt_pk_bf16_f32 v8, v144, v145
	v_cvt_pk_bf16_f32 v9, v146, v147
	v_cvt_pk_bf16_f32 v10, v148, v149
	v_cvt_pk_bf16_f32 v11, v150, v151
	s_nop 0
	global_store_dwordx4 v221, v[8:11], s[28:29]
	s_waitcnt vmcnt(11)
	v_lshlrev_b32_e32 v144, 16, v12
	v_and_b32_e32 v145, 0xffff0000, v12
	v_lshlrev_b32_e32 v152, 16, v44
	v_and_b32_e32 v153, 0xffff0000, v44
	v_lshlrev_b32_e32 v146, 16, v13
	v_and_b32_e32 v147, 0xffff0000, v13
	v_lshlrev_b32_e32 v154, 16, v45
	v_and_b32_e32 v155, 0xffff0000, v45
	v_lshlrev_b32_e32 v148, 16, v14
	v_and_b32_e32 v149, 0xffff0000, v14
	v_lshlrev_b32_e32 v156, 16, v46
	v_and_b32_e32 v157, 0xffff0000, v46
	v_lshlrev_b32_e32 v150, 16, v15
	v_and_b32_e32 v151, 0xffff0000, v15
	v_lshlrev_b32_e32 v158, 16, v47
	v_and_b32_e32 v159, 0xffff0000, v47
	v_sub_f32_e32 v152, v152, v144
	v_sub_f32_e32 v153, v153, v145
	v_sub_f32_e32 v154, v154, v146
	v_sub_f32_e32 v155, v155, v147
	v_sub_f32_e32 v156, v156, v148
	v_sub_f32_e32 v157, v157, v149
	v_sub_f32_e32 v158, v158, v150
	v_sub_f32_e32 v159, v159, v151
	v_fmac_f32_e32 v144, v136, v152
	v_fmac_f32_e32 v145, v137, v153
	v_fmac_f32_e32 v146, v138, v154
	v_fmac_f32_e32 v147, v139, v155
	v_fmac_f32_e32 v148, v140, v156
	v_fmac_f32_e32 v149, v141, v157
	v_fmac_f32_e32 v150, v142, v158
	v_fmac_f32_e32 v151, v143, v159
	v_cvt_pk_bf16_f32 v12, v144, v145
	v_cvt_pk_bf16_f32 v13, v146, v147
	v_cvt_pk_bf16_f32 v14, v148, v149
	v_cvt_pk_bf16_f32 v15, v150, v151
	s_nop 0
	global_store_dwordx4 v222, v[12:15], s[28:29]
	s_waitcnt vmcnt(10)
	v_lshlrev_b32_e32 v144, 16, v16
	v_and_b32_e32 v145, 0xffff0000, v16
	v_lshlrev_b32_e32 v152, 16, v48
	v_and_b32_e32 v153, 0xffff0000, v48
	v_lshlrev_b32_e32 v146, 16, v17
	v_and_b32_e32 v147, 0xffff0000, v17
	v_lshlrev_b32_e32 v154, 16, v49
	v_and_b32_e32 v155, 0xffff0000, v49
	v_lshlrev_b32_e32 v148, 16, v18
	v_and_b32_e32 v149, 0xffff0000, v18
	v_lshlrev_b32_e32 v156, 16, v50
	v_and_b32_e32 v157, 0xffff0000, v50
	v_lshlrev_b32_e32 v150, 16, v19
	v_and_b32_e32 v151, 0xffff0000, v19
	v_lshlrev_b32_e32 v158, 16, v51
	v_and_b32_e32 v159, 0xffff0000, v51
	v_sub_f32_e32 v152, v152, v144
	v_sub_f32_e32 v153, v153, v145
	v_sub_f32_e32 v154, v154, v146
	v_sub_f32_e32 v155, v155, v147
	v_sub_f32_e32 v156, v156, v148
	v_sub_f32_e32 v157, v157, v149
	v_sub_f32_e32 v158, v158, v150
	v_sub_f32_e32 v159, v159, v151
	v_fmac_f32_e32 v144, v136, v152
	v_fmac_f32_e32 v145, v137, v153
	v_fmac_f32_e32 v146, v138, v154
	v_fmac_f32_e32 v147, v139, v155
	v_fmac_f32_e32 v148, v140, v156
	v_fmac_f32_e32 v149, v141, v157
	v_fmac_f32_e32 v150, v142, v158
	v_fmac_f32_e32 v151, v143, v159
	v_cvt_pk_bf16_f32 v16, v144, v145
	v_cvt_pk_bf16_f32 v17, v146, v147
	v_cvt_pk_bf16_f32 v18, v148, v149
	v_cvt_pk_bf16_f32 v19, v150, v151
	s_nop 0
	global_store_dwordx4 v223, v[16:19], s[28:29]
	s_waitcnt vmcnt(9)
	v_lshlrev_b32_e32 v144, 16, v20
	v_and_b32_e32 v145, 0xffff0000, v20
	v_lshlrev_b32_e32 v152, 16, v52
	v_and_b32_e32 v153, 0xffff0000, v52
	v_lshlrev_b32_e32 v146, 16, v21
	v_and_b32_e32 v147, 0xffff0000, v21
	v_lshlrev_b32_e32 v154, 16, v53
	v_and_b32_e32 v155, 0xffff0000, v53
	v_lshlrev_b32_e32 v148, 16, v22
	v_and_b32_e32 v149, 0xffff0000, v22
	v_lshlrev_b32_e32 v156, 16, v54
	v_and_b32_e32 v157, 0xffff0000, v54
	v_lshlrev_b32_e32 v150, 16, v23
	v_and_b32_e32 v151, 0xffff0000, v23
	v_lshlrev_b32_e32 v158, 16, v55
	v_and_b32_e32 v159, 0xffff0000, v55
	v_sub_f32_e32 v152, v152, v144
	v_sub_f32_e32 v153, v153, v145
	v_sub_f32_e32 v154, v154, v146
	v_sub_f32_e32 v155, v155, v147
	v_sub_f32_e32 v156, v156, v148
	v_sub_f32_e32 v157, v157, v149
	v_sub_f32_e32 v158, v158, v150
	v_sub_f32_e32 v159, v159, v151
	v_fmac_f32_e32 v144, v136, v152
	v_fmac_f32_e32 v145, v137, v153
	v_fmac_f32_e32 v146, v138, v154
	v_fmac_f32_e32 v147, v139, v155
	v_fmac_f32_e32 v148, v140, v156
	v_fmac_f32_e32 v149, v141, v157
	v_fmac_f32_e32 v150, v142, v158
	v_fmac_f32_e32 v151, v143, v159
	v_cvt_pk_bf16_f32 v20, v144, v145
	v_cvt_pk_bf16_f32 v21, v146, v147
	v_cvt_pk_bf16_f32 v22, v148, v149
	v_cvt_pk_bf16_f32 v23, v150, v151
	s_nop 0
	global_store_dwordx4 v224, v[20:23], s[28:29]
	s_waitcnt vmcnt(8)
; __device__ __forceinline__ float bf_lo(unsigned u) { return __uint_as_float(u << 16); }
; __device__ __forceinline__ float bf_hi(unsigned u) { return __uint_as_float(u & 0xffff0000u); }
; __device__ __forceinline__ unsigned pk2(float lo, float hi) { return pg8::cvt_pk_bf16(lo, hi); }
; __global__ void __launch_bounds__(NT, 2) mk_fwd(Args args) {
;     ...
;                     for (int op = tid; op < 3 * 32 * 128; op += NT) {
;                         const int which = op >> 12, tl = (op >> 7) & 31, c8 = (op & 127) * 8; const int t = t0 + mt * 32 + tl; const bool first = (t & (SEQ - 1)) == 0;
;                         const bf16* cp = P + (size_t)t * NINP + 2048 + which * 1024 + c8;
;                         const u32x4 cu = *(const u32x4*)cp; u32x4 pr = (u32x4){0u, 0u, 0u, 0u}; if (!first) pr = *(const u32x4*)(cp - NINP);
;                         const f32x4 m0 = *(const f32x4*)(mu + which * 1024 + c8), m1 = *(const f32x4*)(mu + which * 1024 + c8 + 4);
;                         u32x4 o;
;                         { float a = bf_lo(cu.x), b = bf_hi(cu.x); a += (bf_lo(pr.x) - a) * m0.x; b += (bf_hi(pr.x) - b) * m0.y; o.x = pk2(a, b); }
;                         { float a = bf_lo(cu.y), b = bf_hi(cu.y); a += (bf_lo(pr.y) - a) * m0.z; b += (bf_hi(pr.y) - b) * m0.w; o.y = pk2(a, b); }
;                         { float a = bf_lo(cu.z), b = bf_hi(cu.z); a += (bf_lo(pr.z) - a) * m1.x; b += (bf_hi(pr.z) - b) * m1.y; o.z = pk2(a, b); }
;                         { float a = bf_lo(cu.w), b = bf_hi(cu.w); a += (bf_lo(pr.w) - a) * m1.z; b += (bf_hi(pr.w) - b) * m1.w; o.w = pk2(a, b); }
;                         if (which == 0) *(u32x4*)(RR + (size_t)t * 1024 + c8) = o;
;                         else if (which == 2) *(u32x4*)(VV + (size_t)t * 1024 + c8) = o;
;                         else *(u32x4*)(Ks + tl * 1032 + c8) = o;
;                     }
	v_lshlrev_b32_e32 v144, 16, v24
	v_and_b32_e32 v145, 0xffff0000, v24
	v_lshlrev_b32_e32 v152, 16, v56
	v_and_b32_e32 v153, 0xffff0000, v56
	v_lshlrev_b32_e32 v146, 16, v25
	v_and_b32_e32 v147, 0xffff0000, v25
	v_lshlrev_b32_e32 v154, 16, v57
	v_and_b32_e32 v155, 0xffff0000, v57
	v_lshlrev_b32_e32 v148, 16, v26
	v_and_b32_e32 v149, 0xffff0000, v26
	v_lshlrev_b32_e32 v156, 16, v58
	v_and_b32_e32 v157, 0xffff0000, v58
	v_lshlrev_b32_e32 v150, 16, v27
	v_and_b32_e32 v151, 0xffff0000, v27
	v_lshlrev_b32_e32 v158, 16, v59
	v_and_b32_e32 v159, 0xffff0000, v59
	v_sub_f32_e32 v152, v152, v144
	v_sub_f32_e32 v153, v153, v145
	v_sub_f32_e32 v154, v154, v146
	v_sub_f32_e32 v155, v155, v147
	v_sub_f32_e32 v156, v156, v148
	v_sub_f32_e32 v157, v157, v149
	v_sub_f32_e32 v158, v158, v150
	v_sub_f32_e32 v159, v159, v151
	v_fmac_f32_e32 v144, v136, v152
	v_fmac_f32_e32 v145, v137, v153
	v_fmac_f32_e32 v146, v138, v154
	v_fmac_f32_e32 v147, v139, v155
	v_fmac_f32_e32 v148, v140, v156
	v_fmac_f32_e32 v149, v141, v157
	v_fmac_f32_e32 v150, v142, v158
	v_fmac_f32_e32 v151, v143, v159
	v_cvt_pk_bf16_f32 v24, v144, v145
	v_cvt_pk_bf16_f32 v25, v146, v147
	v_cvt_pk_bf16_f32 v26, v148, v149
	v_cvt_pk_bf16_f32 v27, v150, v151
	s_nop 0
	global_store_dwordx4 v225, v[24:27], s[28:29]
	s_waitcnt vmcnt(7)
	v_lshlrev_b32_e32 v144, 16, v28
	v_and_b32_e32 v145, 0xffff0000, v28
	v_lshlrev_b32_e32 v152, 16, v60
	v_and_b32_e32 v153, 0xffff0000, v60
	v_lshlrev_b32_e32 v146, 16, v29
	v_and_b32_e32 v147, 0xffff0000, v29
	v_lshlrev_b32_e32 v154, 16, v61
	v_and_b32_e32 v155, 0xffff0000, v61
	v_lshlrev_b32_e32 v148, 16, v30
	v_and_b32_e32 v149, 0xffff0000, v30
	v_lshlrev_b32_e32 v156, 16, v62
	v_and_b32_e32 v157, 0xffff0000, v62
	v_lshlrev_b32_e32 v150, 16, v31
	v_and_b32_e32 v151, 0xffff0000, v31
	v_lshlrev_b32_e32 v158, 16, v63
	v_and_b32_e32 v159, 0xffff0000, v63
	v_sub_f32_e32 v152, v152, v144
	v_sub_f32_e32 v153, v153, v145
	v_sub_f32_e32 v154, v154, v146
	v_sub_f32_e32 v155, v155, v147
	v_sub_f32_e32 v156, v156, v148
	v_sub_f32_e32 v157, v157, v149
	v_sub_f32_e32 v158, v158, v150
	v_sub_f32_e32 v159, v159, v151
	v_fmac_f32_e32 v144, v136, v152
	v_fmac_f32_e32 v145, v137, v153
	v_fmac_f32_e32 v146, v138, v154
	v_fmac_f32_e32 v147, v139, v155
	v_fmac_f32_e32 v148, v140, v156
	v_fmac_f32_e32 v149, v141, v157
	v_fmac_f32_e32 v150, v142, v158
	v_fmac_f32_e32 v151, v143, v159
	v_cvt_pk_bf16_f32 v28, v144, v145
	v_cvt_pk_bf16_f32 v29, v146, v147
	v_cvt_pk_bf16_f32 v30, v148, v149
	v_cvt_pk_bf16_f32 v31, v150, v151
	s_nop 0
	global_store_dwordx4 v226, v[28:31], s[28:29]
	s_add_u32 s44, s20, 0x1800
	s_addc_u32 s45, s21, 0
	s_sub_u32 s10, s44, 0x2c00
	s_subb_u32 s11, s45, 0
	v_add_u32_e32 v228, 0x1000, v228
	global_load_dwordx4 v[136:139], v228, s[58:59]
	global_load_dwordx4 v[140:143], v228, s[58:59] offset:16
	v_mov_b32_e32 v32, 0
	v_mov_b32_e32 v33, 0
	v_mov_b32_e32 v34, 0
	v_mov_b32_e32 v35, 0
	global_load_dwordx4 v[0:3], v211, s[44:45]
	s_and_saveexec_b64 s[8:9], s[42:43]
	global_load_dwordx4 v[32:35], v211, s[10:11]
	s_or_b64 exec, exec, s[8:9]
	global_load_dwordx4 v[4:7], v212, s[44:45]
	global_load_dwordx4 v[36:39], v212, s[10:11]
	global_load_dwordx4 v[8:11], v213, s[44:45]
	global_load_dwordx4 v[40:43], v213, s[10:11]
	global_load_dwordx4 v[12:15], v214, s[44:45]
	global_load_dwordx4 v[44:47], v214, s[10:11]
	global_load_dwordx4 v[16:19], v215, s[44:45]
	global_load_dwordx4 v[48:51], v215, s[10:11]
	global_load_dwordx4 v[20:23], v216, s[44:45]
	global_load_dwordx4 v[52:55], v216, s[10:11]
	global_load_dwordx4 v[24:27], v217, s[44:45]
	global_load_dwordx4 v[56:59], v217, s[10:11]
	global_load_dwordx4 v[28:31], v218, s[44:45]
	global_load_dwordx4 v[60:63], v218, s[10:11]
	s_waitcnt vmcnt(14)
	v_lshlrev_b32_e32 v144, 16, v0
	v_and_b32_e32 v145, 0xffff0000, v0
	v_lshlrev_b32_e32 v152, 16, v32
	v_and_b32_e32 v153, 0xffff0000, v32
	v_lshlrev_b32_e32 v146, 16, v1
	v_and_b32_e32 v147, 0xffff0000, v1
	v_lshlrev_b32_e32 v154, 16, v33
	v_and_b32_e32 v155, 0xffff0000, v33
	v_lshlrev_b32_e32 v148, 16, v2
	v_and_b32_e32 v149, 0xffff0000, v2
	v_lshlrev_b32_e32 v156, 16, v34
	v_and_b32_e32 v157, 0xffff0000, v34
	v_lshlrev_b32_e32 v150, 16, v3
	v_and_b32_e32 v151, 0xffff0000, v3
	v_lshlrev_b32_e32 v158, 16, v35
	v_and_b32_e32 v159, 0xffff0000, v35
	v_sub_f32_e32 v152, v152, v144
	v_sub_f32_e32 v153, v153, v145
	v_sub_f32_e32 v154, v154, v146
	v_sub_f32_e32 v155, v155, v147
	v_sub_f32_e32 v156, v156, v148
	v_sub_f32_e32 v157, v157, v149
	v_sub_f32_e32 v158, v158, v150
	v_sub_f32_e32 v159, v159, v151
	v_fmac_f32_e32 v144, v136, v152
	v_fmac_f32_e32 v145, v137, v153
	v_fmac_f32_e32 v146, v138, v154
	v_fmac_f32_e32 v147, v139, v155
	v_fmac_f32_e32 v148, v140, v156
	v_fmac_f32_e32 v149, v141, v157
	v_fmac_f32_e32 v150, v142, v158
	v_fmac_f32_e32 v151, v143, v159
	v_cvt_pk_bf16_f32 v0, v144, v145
	v_cvt_pk_bf16_f32 v1, v146, v147
	v_cvt_pk_bf16_f32 v2, v148, v149
	v_cvt_pk_bf16_f32 v3, v150, v151
	s_nop 0
	ds_write_b128 v229, v[0:3] offset:0
	s_waitcnt vmcnt(12)
	v_lshlrev_b32_e32 v144, 16, v4
	v_and_b32_e32 v145, 0xffff0000, v4
	v_lshlrev_b32_e32 v152, 16, v36
	v_and_b32_e32 v153, 0xffff0000, v36
	v_lshlrev_b32_e32 v146, 16, v5
	v_and_b32_e32 v147, 0xffff0000, v5
	v_lshlrev_b32_e32 v154, 16, v37
	v_and_b32_e32 v155, 0xffff0000, v37
	v_lshlrev_b32_e32 v148, 16, v6
	v_and_b32_e32 v149, 0xffff0000, v6
	v_lshlrev_b32_e32 v156, 16, v38
	v_and_b32_e32 v157, 0xffff0000, v38
	v_lshlrev_b32_e32 v150, 16, v7
	v_and_b32_e32 v151, 0xffff0000, v7
	v_lshlrev_b32_e32 v158, 16, v39
	v_and_b32_e32 v159, 0xffff0000, v39
	v_sub_f32_e32 v152, v152, v144
	v_sub_f32_e32 v153, v153, v145
	v_sub_f32_e32 v154, v154, v146
	v_sub_f32_e32 v155, v155, v147
	v_sub_f32_e32 v156, v156, v148
	v_sub_f32_e32 v157, v157, v149
	v_sub_f32_e32 v158, v158, v150
	v_sub_f32_e32 v159, v159, v151
	v_fmac_f32_e32 v144, v136, v152
	v_fmac_f32_e32 v145, v137, v153
	v_fmac_f32_e32 v146, v138, v154
	v_fmac_f32_e32 v147, v139, v155
	v_fmac_f32_e32 v148, v140, v156
	v_fmac_f32_e32 v149, v141, v157
	v_fmac_f32_e32 v150, v142, v158
	v_fmac_f32_e32 v151, v143, v159
	v_cvt_pk_bf16_f32 v4, v144, v145
	v_cvt_pk_bf16_f32 v5, v146, v147
	v_cvt_pk_bf16_f32 v6, v148, v149
	v_cvt_pk_bf16_f32 v7, v150, v151
	s_nop 0
	ds_write_b128 v229, v[4:7] offset:8256
	s_waitcnt vmcnt(10)
; __device__ __forceinline__ float bf_lo(unsigned u) { return __uint_as_float(u << 16); }
; __device__ __forceinline__ float bf_hi(unsigned u) { return __uint_as_float(u & 0xffff0000u); }
; __device__ __forceinline__ unsigned pk2(float lo, float hi) { return pg8::cvt_pk_bf16(lo, hi); }
; __global__ void __launch_bounds__(NT, 2) mk_fwd(Args args) {
;     ...
;                     for (int op = tid; op < 3 * 32 * 128; op += NT) {
;                         const int which = op >> 12, tl = (op >> 7) & 31, c8 = (op & 127) * 8; const int t = t0 + mt * 32 + tl; const bool first = (t & (SEQ - 1)) == 0;
;                         const bf16* cp = P + (size_t)t * NINP + 2048 + which * 1024 + c8;
;                         const u32x4 cu = *(const u32x4*)cp; u32x4 pr = (u32x4){0u, 0u, 0u, 0u}; if (!first) pr = *(const u32x4*)(cp - NINP);
;                         const f32x4 m0 = *(const f32x4*)(mu + which * 1024 + c8), m1 = *(const f32x4*)(mu + which * 1024 + c8 + 4);
;                         u32x4 o;
;                         { float a = bf_lo(cu.x), b = bf_hi(cu.x); a += (bf_lo(pr.x) - a) * m0.x; b += (bf_hi(pr.x) - b) * m0.y; o.x = pk2(a, b); }
;                         { float a = bf_lo(cu.y), b = bf_hi(cu.y); a += (bf_lo(pr.y) - a) * m0.z; b += (bf_hi(pr.y) - b) * m0.w; o.y = pk2(a, b); }
;                         { float a = bf_lo(cu.z), b = bf_hi(cu.z); a += (bf_lo(pr.z) - a) * m1.x; b += (bf_hi(pr.z) - b) * m1.y; o.z = pk2(a, b); }
;                         { float a = bf_lo(cu.w), b = bf_hi(cu.w); a += (bf_lo(pr.w) - a) * m1.z; b += (bf_hi(pr.w) - b) * m1.w; o.w = pk2(a, b); }
;                         if (which == 0) *(u32x4*)(RR + (size_t)t * 1024 + c8) = o;
;                         else if (which == 2) *(u32x4*)(VV + (size_t)t * 1024 + c8) = o;
;                         else *(u32x4*)(Ks + tl * 1032 + c8) = o;
;                     }
	v_lshlrev_b32_e32 v144, 16, v8
	v_and_b32_e32 v145, 0xffff0000, v8
	v_lshlrev_b32_e32 v152, 16, v40
	v_and_b32_e32 v153, 0xffff0000, v40
	v_lshlrev_b32_e32 v146, 16, v9
	v_and_b32_e32 v147, 0xffff0000, v9
	v_lshlrev_b32_e32 v154, 16, v41
	v_and_b32_e32 v155, 0xffff0000, v41
	v_lshlrev_b32_e32 v148, 16, v10
	v_and_b32_e32 v149, 0xffff0000, v10
	v_lshlrev_b32_e32 v156, 16, v42
	v_and_b32_e32 v157, 0xffff0000, v42
	v_lshlrev_b32_e32 v150, 16, v11
	v_and_b32_e32 v151, 0xffff0000, v11
	v_lshlrev_b32_e32 v158, 16, v43
	v_and_b32_e32 v159, 0xffff0000, v43
	v_sub_f32_e32 v152, v152, v144
	v_sub_f32_e32 v153, v153, v145
	v_sub_f32_e32 v154, v154, v146
	v_sub_f32_e32 v155, v155, v147
	v_sub_f32_e32 v156, v156, v148
	v_sub_f32_e32 v157, v157, v149
	v_sub_f32_e32 v158, v158, v150
	v_sub_f32_e32 v159, v159, v151
	v_fmac_f32_e32 v144, v136, v152
	v_fmac_f32_e32 v145, v137, v153
	v_fmac_f32_e32 v146, v138, v154
	v_fmac_f32_e32 v147, v139, v155
	v_fmac_f32_e32 v148, v140, v156
	v_fmac_f32_e32 v149, v141, v157
	v_fmac_f32_e32 v150, v142, v158
	v_fmac_f32_e32 v151, v143, v159
	v_cvt_pk_bf16_f32 v8, v144, v145
	v_cvt_pk_bf16_f32 v9, v146, v147
	v_cvt_pk_bf16_f32 v10, v148, v149
	v_cvt_pk_bf16_f32 v11, v150, v151
	s_nop 0
	ds_write_b128 v229, v[8:11] offset:16512
	s_waitcnt vmcnt(8)
	v_lshlrev_b32_e32 v144, 16, v12
	v_and_b32_e32 v145, 0xffff0000, v12
	v_lshlrev_b32_e32 v152, 16, v44
	v_and_b32_e32 v153, 0xffff0000, v44
	v_lshlrev_b32_e32 v146, 16, v13
	v_and_b32_e32 v147, 0xffff0000, v13
	v_lshlrev_b32_e32 v154, 16, v45
	v_and_b32_e32 v155, 0xffff0000, v45
	v_lshlrev_b32_e32 v148, 16, v14
	v_and_b32_e32 v149, 0xffff0000, v14
	v_lshlrev_b32_e32 v156, 16, v46
	v_and_b32_e32 v157, 0xffff0000, v46
	v_lshlrev_b32_e32 v150, 16, v15
	v_and_b32_e32 v151, 0xffff0000, v15
	v_lshlrev_b32_e32 v158, 16, v47
	v_and_b32_e32 v159, 0xffff0000, v47
	v_sub_f32_e32 v152, v152, v144
	v_sub_f32_e32 v153, v153, v145
	v_sub_f32_e32 v154, v154, v146
	v_sub_f32_e32 v155, v155, v147
	v_sub_f32_e32 v156, v156, v148
	v_sub_f32_e32 v157, v157, v149
	v_sub_f32_e32 v158, v158, v150
	v_sub_f32_e32 v159, v159, v151
	v_fmac_f32_e32 v144, v136, v152
	v_fmac_f32_e32 v145, v137, v153
	v_fmac_f32_e32 v146, v138, v154
	v_fmac_f32_e32 v147, v139, v155
	v_fmac_f32_e32 v148, v140, v156
	v_fmac_f32_e32 v149, v141, v157
	v_fmac_f32_e32 v150, v142, v158
	v_fmac_f32_e32 v151, v143, v159
	v_cvt_pk_bf16_f32 v12, v144, v145
	v_cvt_pk_bf16_f32 v13, v146, v147
	v_cvt_pk_bf16_f32 v14, v148, v149
	v_cvt_pk_bf16_f32 v15, v150, v151
	s_nop 0
	ds_write_b128 v229, v[12:15] offset:24768
	s_waitcnt vmcnt(6)
	v_lshlrev_b32_e32 v144, 16, v16
	v_and_b32_e32 v145, 0xffff0000, v16
	v_lshlrev_b32_e32 v152, 16, v48
	v_and_b32_e32 v153, 0xffff0000, v48
	v_lshlrev_b32_e32 v146, 16, v17
	v_and_b32_e32 v147, 0xffff0000, v17
	v_lshlrev_b32_e32 v154, 16, v49
	v_and_b32_e32 v155, 0xffff0000, v49
	v_lshlrev_b32_e32 v148, 16, v18
	v_and_b32_e32 v149, 0xffff0000, v18
	v_lshlrev_b32_e32 v156, 16, v50
	v_and_b32_e32 v157, 0xffff0000, v50
	v_lshlrev_b32_e32 v150, 16, v19
	v_and_b32_e32 v151, 0xffff0000, v19
	v_lshlrev_b32_e32 v158, 16, v51
	v_and_b32_e32 v159, 0xffff0000, v51
	v_sub_f32_e32 v152, v152, v144
	v_sub_f32_e32 v153, v153, v145
	v_sub_f32_e32 v154, v154, v146
	v_sub_f32_e32 v155, v155, v147
	v_sub_f32_e32 v156, v156, v148
	v_sub_f32_e32 v157, v157, v149
	v_sub_f32_e32 v158, v158, v150
	v_sub_f32_e32 v159, v159, v151
	v_fmac_f32_e32 v144, v136, v152
	v_fmac_f32_e32 v145, v137, v153
	v_fmac_f32_e32 v146, v138, v154
	v_fmac_f32_e32 v147, v139, v155
	v_fmac_f32_e32 v148, v140, v156
	v_fmac_f32_e32 v149, v141, v157
	v_fmac_f32_e32 v150, v142, v158
	v_fmac_f32_e32 v151, v143, v159
	v_cvt_pk_bf16_f32 v16, v144, v145
	v_cvt_pk_bf16_f32 v17, v146, v147
	v_cvt_pk_bf16_f32 v18, v148, v149
	v_cvt_pk_bf16_f32 v19, v150, v151
	s_nop 0
	ds_write_b128 v229, v[16:19] offset:33024
	s_waitcnt vmcnt(4)
	v_lshlrev_b32_e32 v144, 16, v20
	v_and_b32_e32 v145, 0xffff0000, v20
	v_lshlrev_b32_e32 v152, 16, v52
	v_and_b32_e32 v153, 0xffff0000, v52
	v_lshlrev_b32_e32 v146, 16, v21
	v_and_b32_e32 v147, 0xffff0000, v21
	v_lshlrev_b32_e32 v154, 16, v53
	v_and_b32_e32 v155, 0xffff0000, v53
	v_lshlrev_b32_e32 v148, 16, v22
	v_and_b32_e32 v149, 0xffff0000, v22
	v_lshlrev_b32_e32 v156, 16, v54
	v_and_b32_e32 v157, 0xffff0000, v54
	v_lshlrev_b32_e32 v150, 16, v23
	v_and_b32_e32 v151, 0xffff0000, v23
	v_lshlrev_b32_e32 v158, 16, v55
	v_and_b32_e32 v159, 0xffff0000, v55
	v_sub_f32_e32 v152, v152, v144
	v_sub_f32_e32 v153, v153, v145
	v_sub_f32_e32 v154, v154, v146
	v_sub_f32_e32 v155, v155, v147
	v_sub_f32_e32 v156, v156, v148
	v_sub_f32_e32 v157, v157, v149
	v_sub_f32_e32 v158, v158, v150
	v_sub_f32_e32 v159, v159, v151
	v_fmac_f32_e32 v144, v136, v152
	v_fmac_f32_e32 v145, v137, v153
	v_fmac_f32_e32 v146, v138, v154
	v_fmac_f32_e32 v147, v139, v155
	v_fmac_f32_e32 v148, v140, v156
	v_fmac_f32_e32 v149, v141, v157
	v_fmac_f32_e32 v150, v142, v158
	v_fmac_f32_e32 v151, v143, v159
	v_cvt_pk_bf16_f32 v20, v144, v145
	v_cvt_pk_bf16_f32 v21, v146, v147
	v_cvt_pk_bf16_f32 v22, v148, v149
	v_cvt_pk_bf16_f32 v23, v150, v151
	s_nop 0
	ds_write_b128 v229, v[20:23] offset:41280
	s_waitcnt vmcnt(2)
; __device__ __forceinline__ float bf_lo(unsigned u) { return __uint_as_float(u << 16); }
; __device__ __forceinline__ float bf_hi(unsigned u) { return __uint_as_float(u & 0xffff0000u); }
; __device__ __forceinline__ unsigned pk2(float lo, float hi) { return pg8::cvt_pk_bf16(lo, hi); }
; __global__ void __launch_bounds__(NT, 2) mk_fwd(Args args) {
;     ...
;                     for (int op = tid; op < 3 * 32 * 128; op += NT) {
;                         const int which = op >> 12, tl = (op >> 7) & 31, c8 = (op & 127) * 8; const int t = t0 + mt * 32 + tl; const bool first = (t & (SEQ - 1)) == 0;
;                         const bf16* cp = P + (size_t)t * NINP + 2048 + which * 1024 + c8;
;                         const u32x4 cu = *(const u32x4*)cp; u32x4 pr = (u32x4){0u, 0u, 0u, 0u}; if (!first) pr = *(const u32x4*)(cp - NINP);
;                         const f32x4 m0 = *(const f32x4*)(mu + which * 1024 + c8), m1 = *(const f32x4*)(mu + which * 1024 + c8 + 4);
;                         u32x4 o;
;                         { float a = bf_lo(cu.x), b = bf_hi(cu.x); a += (bf_lo(pr.x) - a) * m0.x; b += (bf_hi(pr.x) - b) * m0.y; o.x = pk2(a, b); }
;                         { float a = bf_lo(cu.y), b = bf_hi(cu.y); a += (bf_lo(pr.y) - a) * m0.z; b += (bf_hi(pr.y) - b) * m0.w; o.y = pk2(a, b); }
;                         { float a = bf_lo(cu.z), b = bf_hi(cu.z); a += (bf_lo(pr.z) - a) * m1.x; b += (bf_hi(pr.z) - b) * m1.y; o.z = pk2(a, b); }
;                         { float a = bf_lo(cu.w), b = bf_hi(cu.w); a += (bf_lo(pr.w) - a) * m1.z; b += (bf_hi(pr.w) - b) * m1.w; o.w = pk2(a, b); }
;                         if (which == 0) *(u32x4*)(RR + (size_t)t * 1024 + c8) = o;
;                         else if (which == 2) *(u32x4*)(VV + (size_t)t * 1024 + c8) = o;
;                         else *(u32x4*)(Ks + tl * 1032 + c8) = o;
;                     }
	v_lshlrev_b32_e32 v144, 16, v24
	v_and_b32_e32 v145, 0xffff0000, v24
	v_lshlrev_b32_e32 v152, 16, v56
	v_and_b32_e32 v153, 0xffff0000, v56
	v_lshlrev_b32_e32 v146, 16, v25
	v_and_b32_e32 v147, 0xffff0000, v25
	v_lshlrev_b32_e32 v154, 16, v57
	v_and_b32_e32 v155, 0xffff0000, v57
	v_lshlrev_b32_e32 v148, 16, v26
	v_and_b32_e32 v149, 0xffff0000, v26
	v_lshlrev_b32_e32 v156, 16, v58
	v_and_b32_e32 v157, 0xffff0000, v58
	v_lshlrev_b32_e32 v150, 16, v27
	v_and_b32_e32 v151, 0xffff0000, v27
	v_lshlrev_b32_e32 v158, 16, v59
	v_and_b32_e32 v159, 0xffff0000, v59
	v_sub_f32_e32 v152, v152, v144
	v_sub_f32_e32 v153, v153, v145
	v_sub_f32_e32 v154, v154, v146
	v_sub_f32_e32 v155, v155, v147
	v_sub_f32_e32 v156, v156, v148
	v_sub_f32_e32 v157, v157, v149
	v_sub_f32_e32 v158, v158, v150
	v_sub_f32_e32 v159, v159, v151
	v_fmac_f32_e32 v144, v136, v152
	v_fmac_f32_e32 v145, v137, v153
	v_fmac_f32_e32 v146, v138, v154
	v_fmac_f32_e32 v147, v139, v155
	v_fmac_f32_e32 v148, v140, v156
	v_fmac_f32_e32 v149, v141, v157
	v_fmac_f32_e32 v150, v142, v158
	v_fmac_f32_e32 v151, v143, v159
	v_cvt_pk_bf16_f32 v24, v144, v145
	v_cvt_pk_bf16_f32 v25, v146, v147
	v_cvt_pk_bf16_f32 v26, v148, v149
	v_cvt_pk_bf16_f32 v27, v150, v151
	s_nop 0
	ds_write_b128 v229, v[24:27] offset:49536
	s_waitcnt vmcnt(0)
	v_lshlrev_b32_e32 v144, 16, v28
	v_and_b32_e32 v145, 0xffff0000, v28
	v_lshlrev_b32_e32 v152, 16, v60
	v_and_b32_e32 v153, 0xffff0000, v60
	v_lshlrev_b32_e32 v146, 16, v29
	v_and_b32_e32 v147, 0xffff0000, v29
	v_lshlrev_b32_e32 v154, 16, v61
	v_and_b32_e32 v155, 0xffff0000, v61
	v_lshlrev_b32_e32 v148, 16, v30
	v_and_b32_e32 v149, 0xffff0000, v30
	v_lshlrev_b32_e32 v156, 16, v62
	v_and_b32_e32 v157, 0xffff0000, v62
	v_lshlrev_b32_e32 v150, 16, v31
	v_and_b32_e32 v151, 0xffff0000, v31
	v_lshlrev_b32_e32 v158, 16, v63
	v_and_b32_e32 v159, 0xffff0000, v63
	v_sub_f32_e32 v152, v152, v144
	v_sub_f32_e32 v153, v153, v145
	v_sub_f32_e32 v154, v154, v146
	v_sub_f32_e32 v155, v155, v147
	v_sub_f32_e32 v156, v156, v148
	v_sub_f32_e32 v157, v157, v149
	v_sub_f32_e32 v158, v158, v150
	v_sub_f32_e32 v159, v159, v151
	v_fmac_f32_e32 v144, v136, v152
	v_fmac_f32_e32 v145, v137, v153
	v_fmac_f32_e32 v146, v138, v154
	v_fmac_f32_e32 v147, v139, v155
	v_fmac_f32_e32 v148, v140, v156
	v_fmac_f32_e32 v149, v141, v157
	v_fmac_f32_e32 v150, v142, v158
	v_fmac_f32_e32 v151, v143, v159
	v_cvt_pk_bf16_f32 v28, v144, v145
	v_cvt_pk_bf16_f32 v29, v146, v147
	v_cvt_pk_bf16_f32 v30, v148, v149
	v_cvt_pk_bf16_f32 v31, v150, v151
	s_nop 0
	ds_write_b128 v229, v[28:31] offset:57792
	s_add_u32 s44, s20, 0x2000
	s_addc_u32 s45, s21, 0
	s_sub_u32 s10, s44, 0x2c00
	s_subb_u32 s11, s45, 0
	v_add_u32_e32 v228, 0x1000, v228
	global_load_dwordx4 v[136:139], v228, s[58:59]
	global_load_dwordx4 v[140:143], v228, s[58:59] offset:16
	v_mov_b32_e32 v32, 0
	v_mov_b32_e32 v33, 0
	v_mov_b32_e32 v34, 0
	v_mov_b32_e32 v35, 0
	global_load_dwordx4 v[0:3], v211, s[44:45]
	s_and_saveexec_b64 s[8:9], s[42:43]
	global_load_dwordx4 v[32:35], v211, s[10:11]
	s_or_b64 exec, exec, s[8:9]
	global_load_dwordx4 v[4:7], v212, s[44:45]
	global_load_dwordx4 v[36:39], v212, s[10:11]
	global_load_dwordx4 v[8:11], v213, s[44:45]
	global_load_dwordx4 v[40:43], v213, s[10:11]
	global_load_dwordx4 v[12:15], v214, s[44:45]
	global_load_dwordx4 v[44:47], v214, s[10:11]
	global_load_dwordx4 v[16:19], v215, s[44:45]
	global_load_dwordx4 v[48:51], v215, s[10:11]
	global_load_dwordx4 v[20:23], v216, s[44:45]
	global_load_dwordx4 v[52:55], v216, s[10:11]
	global_load_dwordx4 v[24:27], v217, s[44:45]
	global_load_dwordx4 v[56:59], v217, s[10:11]
	global_load_dwordx4 v[28:31], v218, s[44:45]
	global_load_dwordx4 v[60:63], v218, s[10:11]
	s_waitcnt vmcnt(14)
	v_lshlrev_b32_e32 v144, 16, v0
	v_and_b32_e32 v145, 0xffff0000, v0
	v_lshlrev_b32_e32 v152, 16, v32
	v_and_b32_e32 v153, 0xffff0000, v32
	v_lshlrev_b32_e32 v146, 16, v1
	v_and_b32_e32 v147, 0xffff0000, v1
	v_lshlrev_b32_e32 v154, 16, v33
	v_and_b32_e32 v155, 0xffff0000, v33
	v_lshlrev_b32_e32 v148, 16, v2
	v_and_b32_e32 v149, 0xffff0000, v2
	v_lshlrev_b32_e32 v156, 16, v34
	v_and_b32_e32 v157, 0xffff0000, v34
	v_lshlrev_b32_e32 v150, 16, v3
	v_and_b32_e32 v151, 0xffff0000, v3
	v_lshlrev_b32_e32 v158, 16, v35
	v_and_b32_e32 v159, 0xffff0000, v35
	v_sub_f32_e32 v152, v152, v144
	v_sub_f32_e32 v153, v153, v145
	v_sub_f32_e32 v154, v154, v146
	v_sub_f32_e32 v155, v155, v147
	v_sub_f32_e32 v156, v156, v148
	v_sub_f32_e32 v157, v157, v149
	v_sub_f32_e32 v158, v158, v150
	v_sub_f32_e32 v159, v159, v151
	v_fmac_f32_e32 v144, v136, v152
	v_fmac_f32_e32 v145, v137, v153
	v_fmac_f32_e32 v146, v138, v154
	v_fmac_f32_e32 v147, v139, v155
	v_fmac_f32_e32 v148, v140, v156
	v_fmac_f32_e32 v149, v141, v157
	v_fmac_f32_e32 v150, v142, v158
	v_fmac_f32_e32 v151, v143, v159
	v_cvt_pk_bf16_f32 v0, v144, v145
	v_cvt_pk_bf16_f32 v1, v146, v147
	v_cvt_pk_bf16_f32 v2, v148, v149
	v_cvt_pk_bf16_f32 v3, v150, v151
	s_nop 0
	global_store_dwordx4 v219, v[0:3], s[24:25]
	s_waitcnt vmcnt(13)
	v_lshlrev_b32_e32 v144, 16, v4
	v_and_b32_e32 v145, 0xffff0000, v4
	v_lshlrev_b32_e32 v152, 16, v36
	v_and_b32_e32 v153, 0xffff0000, v36
	v_lshlrev_b32_e32 v146, 16, v5
	v_and_b32_e32 v147, 0xffff0000, v5
	v_lshlrev_b32_e32 v154, 16, v37
	v_and_b32_e32 v155, 0xffff0000, v37
	v_lshlrev_b32_e32 v148, 16, v6
	v_and_b32_e32 v149, 0xffff0000, v6
	v_lshlrev_b32_e32 v156, 16, v38
	v_and_b32_e32 v157, 0xffff0000, v38
	v_lshlrev_b32_e32 v150, 16, v7
	v_and_b32_e32 v151, 0xffff0000, v7
	v_lshlrev_b32_e32 v158, 16, v39
	v_and_b32_e32 v159, 0xffff0000, v39
	v_sub_f32_e32 v152, v152, v144
	v_sub_f32_e32 v153, v153, v145
	v_sub_f32_e32 v154, v154, v146
	v_sub_f32_e32 v155, v155, v147
	v_sub_f32_e32 v156, v156, v148
	v_sub_f32_e32 v157, v157, v149
	v_sub_f32_e32 v158, v158, v150
	v_sub_f32_e32 v159, v159, v151
	v_fmac_f32_e32 v144, v136, v152
	v_fmac_f32_e32 v145, v137, v153
	v_fmac_f32_e32 v146, v138, v154
	v_fmac_f32_e32 v147, v139, v155
	v_fmac_f32_e32 v148, v140, v156
	v_fmac_f32_e32 v149, v141, v157
	v_fmac_f32_e32 v150, v142, v158
	v_fmac_f32_e32 v151, v143, v159
	v_cvt_pk_bf16_f32 v4, v144, v145
	v_cvt_pk_bf16_f32 v5, v146, v147
	v_cvt_pk_bf16_f32 v6, v148, v149
	v_cvt_pk_bf16_f32 v7, v150, v151
	s_nop 0
	global_store_dwordx4 v220, v[4:7], s[24:25]
	s_waitcnt vmcnt(12)
; __device__ __forceinline__ float bf_lo(unsigned u) { return __uint_as_float(u << 16); }
; __device__ __forceinline__ float bf_hi(unsigned u) { return __uint_as_float(u & 0xffff0000u); }
; __device__ __forceinline__ unsigned pk2(float lo, float hi) { return pg8::cvt_pk_bf16(lo, hi); }
; __global__ void __launch_bounds__(NT, 2) mk_fwd(Args args) {
;     ...
;                     for (int op = tid; op < 3 * 32 * 128; op += NT) {
;                         const int which = op >> 12, tl = (op >> 7) & 31, c8 = (op & 127) * 8; const int t = t0 + mt * 32 + tl; const bool first = (t & (SEQ - 1)) == 0;
;                         const bf16* cp = P + (size_t)t * NINP + 2048 + which * 1024 + c8;
;                         const u32x4 cu = *(const u32x4*)cp; u32x4 pr = (u32x4){0u, 0u, 0u, 0u}; if (!first) pr = *(const u32x4*)(cp - NINP);
;                         const f32x4 m0 = *(const f32x4*)(mu + which * 1024 + c8), m1 = *(const f32x4*)(mu + which * 1024 + c8 + 4);
;                         u32x4 o;
;                         { float a = bf_lo(cu.x), b = bf_hi(cu.x); a += (bf_lo(pr.x) - a) * m0.x; b += (bf_hi(pr.x) - b) * m0.y; o.x = pk2(a, b); }
;                         { float a = bf_lo(cu.y), b = bf_hi(cu.y); a += (bf_lo(pr.y) - a) * m0.z; b += (bf_hi(pr.y) - b) * m0.w; o.y = pk2(a, b); }
;                         { float a = bf_lo(cu.z), b = bf_hi(cu.z); a += (bf_lo(pr.z) - a) * m1.x; b += (bf_hi(pr.z) - b) * m1.y; o.z = pk2(a, b); }
;                         { float a = bf_lo(cu.w), b = bf_hi(cu.w); a += (bf_lo(pr.w) - a) * m1.z; b += (bf_hi(pr.w) - b) * m1.w; o.w = pk2(a, b); }
;                         if (which == 0) *(u32x4*)(RR + (size_t)t * 1024 + c8) = o;
;                         else if (which == 2) *(u32x4*)(VV + (size_t)t * 1024 + c8) = o;
;                         else *(u32x4*)(Ks + tl * 1032 + c8) = o;
;                     }
	v_lshlrev_b32_e32 v144, 16, v8
	v_and_b32_e32 v145, 0xffff0000, v8
	v_lshlrev_b32_e32 v152, 16, v40
	v_and_b32_e32 v153, 0xffff0000, v40
	v_lshlrev_b32_e32 v146, 16, v9
	v_and_b32_e32 v147, 0xffff0000, v9
	v_lshlrev_b32_e32 v154, 16, v41
	v_and_b32_e32 v155, 0xffff0000, v41
	v_lshlrev_b32_e32 v148, 16, v10
	v_and_b32_e32 v149, 0xffff0000, v10
	v_lshlrev_b32_e32 v156, 16, v42
	v_and_b32_e32 v157, 0xffff0000, v42
	v_lshlrev_b32_e32 v150, 16, v11
	v_and_b32_e32 v151, 0xffff0000, v11
	v_lshlrev_b32_e32 v158, 16, v43
	v_and_b32_e32 v159, 0xffff0000, v43
	v_sub_f32_e32 v152, v152, v144
	v_sub_f32_e32 v153, v153, v145
	v_sub_f32_e32 v154, v154, v146
	v_sub_f32_e32 v155, v155, v147
	v_sub_f32_e32 v156, v156, v148
	v_sub_f32_e32 v157, v157, v149
	v_sub_f32_e32 v158, v158, v150
	v_sub_f32_e32 v159, v159, v151
	v_fmac_f32_e32 v144, v136, v152
	v_fmac_f32_e32 v145, v137, v153
	v_fmac_f32_e32 v146, v138, v154
	v_fmac_f32_e32 v147, v139, v155
	v_fmac_f32_e32 v148, v140, v156
	v_fmac_f32_e32 v149, v141, v157
	v_fmac_f32_e32 v150, v142, v158
	v_fmac_f32_e32 v151, v143, v159
	v_cvt_pk_bf16_f32 v8, v144, v145
	v_cvt_pk_bf16_f32 v9, v146, v147
	v_cvt_pk_bf16_f32 v10, v148, v149
	v_cvt_pk_bf16_f32 v11, v150, v151
	s_nop 0
	global_store_dwordx4 v221, v[8:11], s[24:25]
	s_waitcnt vmcnt(11)
	v_lshlrev_b32_e32 v144, 16, v12
	v_and_b32_e32 v145, 0xffff0000, v12
	v_lshlrev_b32_e32 v152, 16, v44
	v_and_b32_e32 v153, 0xffff0000, v44
	v_lshlrev_b32_e32 v146, 16, v13
	v_and_b32_e32 v147, 0xffff0000, v13
	v_lshlrev_b32_e32 v154, 16, v45
	v_and_b32_e32 v155, 0xffff0000, v45
	v_lshlrev_b32_e32 v148, 16, v14
	v_and_b32_e32 v149, 0xffff0000, v14
	v_lshlrev_b32_e32 v156, 16, v46
	v_and_b32_e32 v157, 0xffff0000, v46
	v_lshlrev_b32_e32 v150, 16, v15
	v_and_b32_e32 v151, 0xffff0000, v15
	v_lshlrev_b32_e32 v158, 16, v47
	v_and_b32_e32 v159, 0xffff0000, v47
	v_sub_f32_e32 v152, v152, v144
	v_sub_f32_e32 v153, v153, v145
	v_sub_f32_e32 v154, v154, v146
	v_sub_f32_e32 v155, v155, v147
	v_sub_f32_e32 v156, v156, v148
	v_sub_f32_e32 v157, v157, v149
	v_sub_f32_e32 v158, v158, v150
	v_sub_f32_e32 v159, v159, v151
	v_fmac_f32_e32 v144, v136, v152
	v_fmac_f32_e32 v145, v137, v153
	v_fmac_f32_e32 v146, v138, v154
	v_fmac_f32_e32 v147, v139, v155
	v_fmac_f32_e32 v148, v140, v156
	v_fmac_f32_e32 v149, v141, v157
	v_fmac_f32_e32 v150, v142, v158
	v_fmac_f32_e32 v151, v143, v159
	v_cvt_pk_bf16_f32 v12, v144, v145
	v_cvt_pk_bf16_f32 v13, v146, v147
	v_cvt_pk_bf16_f32 v14, v148, v149
	v_cvt_pk_bf16_f32 v15, v150, v151
	s_nop 0
	global_store_dwordx4 v222, v[12:15], s[24:25]
	s_waitcnt vmcnt(10)
	v_lshlrev_b32_e32 v144, 16, v16
	v_and_b32_e32 v145, 0xffff0000, v16
	v_lshlrev_b32_e32 v152, 16, v48
	v_and_b32_e32 v153, 0xffff0000, v48
	v_lshlrev_b32_e32 v146, 16, v17
	v_and_b32_e32 v147, 0xffff0000, v17
	v_lshlrev_b32_e32 v154, 16, v49
	v_and_b32_e32 v155, 0xffff0000, v49
	v_lshlrev_b32_e32 v148, 16, v18
	v_and_b32_e32 v149, 0xffff0000, v18
	v_lshlrev_b32_e32 v156, 16, v50
	v_and_b32_e32 v157, 0xffff0000, v50
	v_lshlrev_b32_e32 v150, 16, v19
	v_and_b32_e32 v151, 0xffff0000, v19
	v_lshlrev_b32_e32 v158, 16, v51
	v_and_b32_e32 v159, 0xffff0000, v51
	v_sub_f32_e32 v152, v152, v144
	v_sub_f32_e32 v153, v153, v145
	v_sub_f32_e32 v154, v154, v146
	v_sub_f32_e32 v155, v155, v147
	v_sub_f32_e32 v156, v156, v148
	v_sub_f32_e32 v157, v157, v149
	v_sub_f32_e32 v158, v158, v150
	v_sub_f32_e32 v159, v159, v151
	v_fmac_f32_e32 v144, v136, v152
	v_fmac_f32_e32 v145, v137, v153
	v_fmac_f32_e32 v146, v138, v154
	v_fmac_f32_e32 v147, v139, v155
	v_fmac_f32_e32 v148, v140, v156
	v_fmac_f32_e32 v149, v141, v157
	v_fmac_f32_e32 v150, v142, v158
	v_fmac_f32_e32 v151, v143, v159
	v_cvt_pk_bf16_f32 v16, v144, v145
	v_cvt_pk_bf16_f32 v17, v146, v147
	v_cvt_pk_bf16_f32 v18, v148, v149
	v_cvt_pk_bf16_f32 v19, v150, v151
	s_nop 0
	global_store_dwordx4 v223, v[16:19], s[24:25]
	s_waitcnt vmcnt(9)
; __device__ __forceinline__ float bf_lo(unsigned u) { return __uint_as_float(u << 16); }
; __device__ __forceinline__ float bf_hi(unsigned u) { return __uint_as_float(u & 0xffff0000u); }
; __device__ __forceinline__ unsigned pk2(float lo, float hi) { return pg8::cvt_pk_bf16(lo, hi); }
; __global__ void __launch_bounds__(NT, 2) mk_fwd(Args args) {
;     ...
;                     for (int op = tid; op < 3 * 32 * 128; op += NT) {
;                         const int which = op >> 12, tl = (op >> 7) & 31, c8 = (op & 127) * 8; const int t = t0 + mt * 32 + tl; const bool first = (t & (SEQ - 1)) == 0;
;                         const bf16* cp = P + (size_t)t * NINP + 2048 + which * 1024 + c8;
;                         const u32x4 cu = *(const u32x4*)cp; u32x4 pr = (u32x4){0u, 0u, 0u, 0u}; if (!first) pr = *(const u32x4*)(cp - NINP);
;                         const f32x4 m0 = *(const f32x4*)(mu + which * 1024 + c8), m1 = *(const f32x4*)(mu + which * 1024 + c8 + 4);
;                         u32x4 o;
;                         { float a = bf_lo(cu.x), b = bf_hi(cu.x); a += (bf_lo(pr.x) - a) * m0.x; b += (bf_hi(pr.x) - b) * m0.y; o.x = pk2(a, b); }
;                         { float a = bf_lo(cu.y), b = bf_hi(cu.y); a += (bf_lo(pr.y) - a) * m0.z; b += (bf_hi(pr.y) - b) * m0.w; o.y = pk2(a, b); }
;                         { float a = bf_lo(cu.z), b = bf_hi(cu.z); a += (bf_lo(pr.z) - a) * m1.x; b += (bf_hi(pr.z) - b) * m1.y; o.z = pk2(a, b); }
;                         { float a = bf_lo(cu.w), b = bf_hi(cu.w); a += (bf_lo(pr.w) - a) * m1.z; b += (bf_hi(pr.w) - b) * m1.w; o.w = pk2(a, b); }
;                         if (which == 0) *(u32x4*)(RR + (size_t)t * 1024 + c8) = o;
;                         else if (which == 2) *(u32x4*)(VV + (size_t)t * 1024 + c8) = o;
;                         else *(u32x4*)(Ks + tl * 1032 + c8) = o;
;                     }
	v_lshlrev_b32_e32 v144, 16, v20
	v_and_b32_e32 v145, 0xffff0000, v20
	v_lshlrev_b32_e32 v152, 16, v52
	v_and_b32_e32 v153, 0xffff0000, v52
	v_lshlrev_b32_e32 v146, 16, v21
	v_and_b32_e32 v147, 0xffff0000, v21
	v_lshlrev_b32_e32 v154, 16, v53
	v_and_b32_e32 v155, 0xffff0000, v53
	v_lshlrev_b32_e32 v148, 16, v22
	v_and_b32_e32 v149, 0xffff0000, v22
	v_lshlrev_b32_e32 v156, 16, v54
	v_and_b32_e32 v157, 0xffff0000, v54
	v_lshlrev_b32_e32 v150, 16, v23
	v_and_b32_e32 v151, 0xffff0000, v23
	v_lshlrev_b32_e32 v158, 16, v55
	v_and_b32_e32 v159, 0xffff0000, v55
	v_sub_f32_e32 v152, v152, v144
	v_sub_f32_e32 v153, v153, v145
	v_sub_f32_e32 v154, v154, v146
	v_sub_f32_e32 v155, v155, v147
	v_sub_f32_e32 v156, v156, v148
	v_sub_f32_e32 v157, v157, v149
	v_sub_f32_e32 v158, v158, v150
	v_sub_f32_e32 v159, v159, v151
	v_fmac_f32_e32 v144, v136, v152
	v_fmac_f32_e32 v145, v137, v153
	v_fmac_f32_e32 v146, v138, v154
	v_fmac_f32_e32 v147, v139, v155
	v_fmac_f32_e32 v148, v140, v156
	v_fmac_f32_e32 v149, v141, v157
	v_fmac_f32_e32 v150, v142, v158
	v_fmac_f32_e32 v151, v143, v159
	v_cvt_pk_bf16_f32 v20, v144, v145
	v_cvt_pk_bf16_f32 v21, v146, v147
	v_cvt_pk_bf16_f32 v22, v148, v149
	v_cvt_pk_bf16_f32 v23, v150, v151
	s_nop 0
	global_store_dwordx4 v224, v[20:23], s[24:25]
	s_waitcnt vmcnt(8)
	v_lshlrev_b32_e32 v144, 16, v24
	v_and_b32_e32 v145, 0xffff0000, v24
	v_lshlrev_b32_e32 v152, 16, v56
	v_and_b32_e32 v153, 0xffff0000, v56
	v_lshlrev_b32_e32 v146, 16, v25
	v_and_b32_e32 v147, 0xffff0000, v25
	v_lshlrev_b32_e32 v154, 16, v57
	v_and_b32_e32 v155, 0xffff0000, v57
	v_lshlrev_b32_e32 v148, 16, v26
	v_and_b32_e32 v149, 0xffff0000, v26
	v_lshlrev_b32_e32 v156, 16, v58
	v_and_b32_e32 v157, 0xffff0000, v58
	v_lshlrev_b32_e32 v150, 16, v27
	v_and_b32_e32 v151, 0xffff0000, v27
	v_lshlrev_b32_e32 v158, 16, v59
	v_and_b32_e32 v159, 0xffff0000, v59
	v_sub_f32_e32 v152, v152, v144
	v_sub_f32_e32 v153, v153, v145
	v_sub_f32_e32 v154, v154, v146
	v_sub_f32_e32 v155, v155, v147
	v_sub_f32_e32 v156, v156, v148
	v_sub_f32_e32 v157, v157, v149
	v_sub_f32_e32 v158, v158, v150
	v_sub_f32_e32 v159, v159, v151
	v_fmac_f32_e32 v144, v136, v152
	v_fmac_f32_e32 v145, v137, v153
	v_fmac_f32_e32 v146, v138, v154
	v_fmac_f32_e32 v147, v139, v155
	v_fmac_f32_e32 v148, v140, v156
	v_fmac_f32_e32 v149, v141, v157
	v_fmac_f32_e32 v150, v142, v158
	v_fmac_f32_e32 v151, v143, v159
	v_cvt_pk_bf16_f32 v24, v144, v145
	v_cvt_pk_bf16_f32 v25, v146, v147
	v_cvt_pk_bf16_f32 v26, v148, v149
	v_cvt_pk_bf16_f32 v27, v150, v151
	s_nop 0
	global_store_dwordx4 v225, v[24:27], s[24:25]
	s_waitcnt vmcnt(7)
	v_lshlrev_b32_e32 v144, 16, v28
	v_and_b32_e32 v145, 0xffff0000, v28
	v_lshlrev_b32_e32 v152, 16, v60
	v_and_b32_e32 v153, 0xffff0000, v60
	v_lshlrev_b32_e32 v146, 16, v29
	v_and_b32_e32 v147, 0xffff0000, v29
	v_lshlrev_b32_e32 v154, 16, v61
	v_and_b32_e32 v155, 0xffff0000, v61
	v_lshlrev_b32_e32 v148, 16, v30
	v_and_b32_e32 v149, 0xffff0000, v30
	v_lshlrev_b32_e32 v156, 16, v62
	v_and_b32_e32 v157, 0xffff0000, v62
	v_lshlrev_b32_e32 v150, 16, v31
	v_and_b32_e32 v151, 0xffff0000, v31
	v_lshlrev_b32_e32 v158, 16, v63
	v_and_b32_e32 v159, 0xffff0000, v63
	v_sub_f32_e32 v152, v152, v144
	v_sub_f32_e32 v153, v153, v145
	v_sub_f32_e32 v154, v154, v146
	v_sub_f32_e32 v155, v155, v147
	v_sub_f32_e32 v156, v156, v148
	v_sub_f32_e32 v157, v157, v149
	v_sub_f32_e32 v158, v158, v150
	v_sub_f32_e32 v159, v159, v151
	v_fmac_f32_e32 v144, v136, v152
	v_fmac_f32_e32 v145, v137, v153
	v_fmac_f32_e32 v146, v138, v154
	v_fmac_f32_e32 v147, v139, v155
	v_fmac_f32_e32 v148, v140, v156
	v_fmac_f32_e32 v149, v141, v157
	v_fmac_f32_e32 v150, v142, v158
	v_fmac_f32_e32 v151, v143, v159
	v_cvt_pk_bf16_f32 v28, v144, v145
	v_cvt_pk_bf16_f32 v29, v146, v147
	v_cvt_pk_bf16_f32 v30, v148, v149
	v_cvt_pk_bf16_f32 v31, v150, v151
	s_nop 0
	global_store_dwordx4 v226, v[28:31], s[24:25]
	s_mov_b64 s[8:9], 0
